# v50: v46 with barrier poll interval s_sleep 4 and a slower poll (s_sleep 3) in the up-tail hand-off spin of the merged down phase
# speedup vs baseline: 1.0055x; 1.0055x over previous
.Lxb0_wait:
	global_load_dword v248, v253, s[60:61] sc1
	v_add_u32_e32 v252, 1, v252
	s_waitcnt vmcnt(0)
	v_cmp_ge_u32_e32 vcc, v248, v249
	s_cbranch_vccnz .Lxb0_wdone
	v_cmp_gt_u32_e32 vcc, 0x100000, v252
	s_cbranch_vccz .Lxb0_wdone
	s_sleep 4
	s_branch .Lxb0_wait

.LBB0_3474:
	s_and_b32 s10, s17, 0xff
	s_mov_b64 s[8:9], -1
	s_cmp_lg_u32 s10, 0
	s_mov_b64 s[14:15], -1
	s_sleep 3
	s_cbranch_scc0 .LBB0_3477
	s_and_b64 vcc, exec, s[14:15]
	s_cbranch_vccz .LBB0_3473
